# out-proj->gate-up and down->in-proj grid barriers replaced by a 4-workgroup same-row-panel counter sync (run-time check that the partners share an XCC, else the grid barrier is kept)
# speedup vs baseline: 1.0108x; 1.0108x over previous
.LBB0_443:
	s_cmp_lg_u32 s96, 0
	s_cbranch_scc1 .Lgp_skip
	v_readlane_b32 s0, v252, 5
	s_nop 0
	s_cmp_lg_u32 s0, 0
	s_cbranch_scc1 .Lgp_skip
	s_getreg_b32 s0, hwreg(HW_REG_XCC_ID, 0, 4)
	s_and_b32 s0, s0, 7
	s_lshl_b32 s0, s0, 2
	s_lshl_b32 s0, 1, s0
	v_mov_b32_e32 v0, s0
	v_readlane_b32 s0, v252, 0
	s_nop 0
	s_and_b32 s0, s0, 63
	s_lshl_b32 s0, s0, 2
	s_add_u32 s0, s0, 0x13500100
	s_add_u32 s0, s40, s0
	s_addc_u32 s1, s41, 0
	s_mov_b64 exec, 1
	global_atomic_add v65, v0, s[0:1]
	s_mov_b64 exec, -1

.LBB0_445:
	s_nop 0
	s_mul_i32 s0, s96, 7
	s_add_i32 s4, s0, 1
	s_cmp_ge_i32 s4, s92
	v_writelane_b32 v255, s0, 8
	s_cselect_b64 s[0:1], -1, 0
	s_cmp_lt_i32 s4, s93
	s_cselect_b64 s[4:5], -1, 0
	s_and_b64 s[4:5], s[0:1], s[4:5]
	s_mov_b64 s[0:1], -1
	s_and_b64 vcc, exec, s[4:5]
	s_cbranch_vccnz .LBB0_447
	s_mul_i32 s0, s96, 7
	s_add_i32 s26, s0, 2
	s_mov_b64 s[0:1], 0

.LBB0_892:
	s_cmp_lg_u32 s96, 0
	s_cbranch_scc1 .Lgc_skip
	v_readlane_b32 s0, v252, 5
	s_nop 0
	s_cmp_lg_u32 s0, 0
	s_cbranch_scc1 .Lgc_skip
	v_readlane_b32 s0, v252, 0
	s_nop 0
	s_and_b32 s0, s0, 63
	s_lshl_b32 s0, s0, 2
	s_add_u32 s0, s0, 0x13500100
	s_add_u32 s0, s40, s0
	s_addc_u32 s1, s41, 0
	global_load_dword v0, v65, s[0:1] sc1
	s_getreg_b32 s4, hwreg(HW_REG_XCC_ID, 0, 4)
	s_and_b32 s4, s4, 15
	s_cmp_gt_u32 s4, 7
	s_cbranch_scc1 .Lgc_bad
	s_lshl_b32 s4, s4, 2
	s_lshl_b32 s4, 4, s4
	v_mov_b32_e32 v1, s4
	s_waitcnt vmcnt(0)
	v_cmp_eq_u32_e32 vcc, v0, v1
	s_cbranch_vccnz .Lgc_skip
.Lgc_bad:
	s_waitcnt vmcnt(0)
	s_add_u32 s0, s40, 0x13503404
	s_addc_u32 s1, s41, 0
	v_mov_b32_e32 v0, 1
	s_mov_b64 exec, 1
	global_atomic_add v65, v0, s[0:1]
	s_mov_b64 exec, -1
.Lgc_skip:
	v_readlane_b32 s0, v252, 5
	s_nop 0
	s_cmp_ge_u32 s0, 0x100
	s_cbranch_scc0 .Lprio_att
	s_setprio 1

.LBB0_894:
	s_nop 0
	s_andn2_b64 vcc, exec, s[0:1]
	v_mov_b32_e32 v202, v200
	s_cbranch_vccnz .LBB0_1145
	v_cvt_f32_u32_e32 v0, s96
	s_mov_b32 s0, 0x3fb8aa3b
	s_lshl_b32 s4, s96, 6
	v_mul_f32_e32 v0, 0xbe99999a, v0
	s_waitcnt lgkmcnt(0)
	v_mul_f32_e32 v1, 0x3fb8aa3b, v0
	v_fma_f32 v2, v0, s0, -v1
	v_rndne_f32_e32 v3, v1
	v_fmac_f32_e32 v2, 0x32a5705f, v0
	v_sub_f32_e32 v1, v1, v3
	v_add_f32_e32 v1, v1, v2
	v_cvt_i32_f32_e32 v3, v3
	v_exp_f32_e32 v1, v1
	s_mov_b32 s0, 0xc2ce8ed0
	v_cmp_ngt_f32_e32 vcc, s0, v0
	s_mov_b32 s0, 0x42b17218
	v_ldexp_f32 v1, v1, v3
	v_cndmask_b32_e32 v1, 0, v1, vcc
	v_cmp_nlt_f32_e32 vcc, s0, v0
	v_readlane_b32 s0, v254, 43
	v_readlane_b32 s1, v254, 44
	s_mov_b32 s5, s1
	v_mov_b32_e32 v0, 0x7f800000
	v_writelane_b32 v255, s4, 10
	v_cndmask_b32_e32 v0, v0, v1, vcc
	v_mov_b32_e32 v1, 0x3f4ccccd
	v_writelane_b32 v255, s5, 11
	v_readlane_b32 s4, v253, 27
	v_fmamk_f32 v168, v0, 0xbf19999a, v1
	v_readlane_b32 s5, v253, 28
	v_sub_f32_e32 v163, 1.0, v168
	s_mov_b64 s[0:1], -1
	s_and_b64 vcc, exec, s[4:5]
	s_cbranch_vccz .LBB0_983
	v_readlane_b32 s0, v254, 0
	v_readlane_b32 s1, v254, 1
	s_andn2_b64 vcc, exec, s[0:1]
	s_cbranch_vccnz .LBB0_982
	s_mov_b32 s30, 0
	s_branch .LBB0_900

.LBB0_1184:
	v_readlane_b32 s0, v255, 8
	s_add_i32 s26, s0, 6
	s_cmp_ge_i32 s26, s93
	s_cbranch_scc1 .LBB0_1240
	s_waitcnt vmcnt(0)
	v_readlane_b32 s0, v252, 3
	v_readlane_b32 s1, v252, 4
	s_and_b64 vcc, exec, s[0:1]
	s_waitcnt lgkmcnt(0)
	s_barrier
	s_cbranch_vccnz .LBB0_1239
	s_cmp_lg_u32 s96, 0
	s_cbranch_scc1 .LgA_have
	s_add_u32 s4, s40, 0x13503404
	s_addc_u32 s5, s41, 0
	global_load_dword v0, v65, s[4:5] sc1
	s_waitcnt vmcnt(0)
	v_readfirstlane_b32 s32, v0
	s_nop 0
	s_cmp_eq_u32 s32, 0
	s_cselect_b32 s32, 1, 0
.LgA_have:
	s_cmp_eq_u32 s32, 1
	s_cbranch_scc0 .LgA_orig
	v_readlane_b32 s4, v252, 0
	s_nop 0
	s_and_b32 s4, s4, 63
	s_lshl_b32 s4, s4, 2
	s_add_u32 s4, s4, 0x13500000
	s_add_u32 s4, s40, s4
	s_addc_u32 s5, s41, 0
	s_lshl_b32 s6, s96, 3
	s_add_i32 s6, s6, 4
	v_mov_b32_e32 v1, 1
	v_mov_b32_e32 v2, s6
	s_mov_b64 exec, 1
	global_atomic_add v65, v1, s[4:5]
	s_mov_b32 s27, 0
.LgA_poll:
	global_load_dword v0, v65, s[4:5] sc1
	s_waitcnt vmcnt(0)
	v_cmp_ge_u32_e32 vcc, v0, v2
	s_cbranch_vccnz .LgA_done
	s_sleep 1
	s_add_i32 s27, s27, 1
	s_cmp_lt_u32 s27, 0x80000
	s_cbranch_scc1 .LgA_poll
.LgA_done:
	buffer_inv sc1
	s_waitcnt vmcnt(0)
	s_mov_b64 s[0:1], -1
	s_branch .LBB0_1238
.LgA_orig:
	s_mov_b32 s0, -1
	s_nop 0
	v_mbcnt_lo_u32_b32 v0, s0, 0
	v_mbcnt_hi_u32_b32 v0, s0, v0
	v_cmp_eq_u32_e32 vcc, 0, v0
	s_and_saveexec_b64 s[0:1], vcc
	s_cbranch_execz .LBB0_1238
	v_readlane_b32 s4, v254, 31
	s_waitcnt vmcnt(0) expcnt(0) lgkmcnt(0)
	s_nop 0
	v_mov_b32_e32 v0, s4
	ds_read_b32 v2, v0
	v_readlane_b32 s4, v254, 32
	s_waitcnt lgkmcnt(0)
	v_cmp_ne_u32_e32 vcc, 0, v2
	v_mov_b32_e32 v0, s4
	ds_read_b32 v0, v0
	s_cbranch_vccnz .LBB0_1202
	s_mov_b32 s27, 1
	s_branch .LBB0_1190

.Lg_to441:
	s_getpc_b64 s[98:99]

.LBB0_1739:
	s_cmp_eq_u32 s32, 1
	s_cbranch_scc0 .LgB_orig
	v_readlane_b32 s4, v252, 0
	s_nop 0
	s_and_b32 s4, s4, 63
	s_lshl_b32 s4, s4, 2
	s_add_u32 s4, s4, 0x13500000
	s_add_u32 s4, s40, s4
	s_addc_u32 s5, s41, 0
	s_lshl_b32 s6, s96, 3
	s_add_i32 s6, s6, 8
	v_mov_b32_e32 v1, 1
	v_mov_b32_e32 v2, s6
	s_mov_b64 exec, 1
	global_atomic_add v65, v1, s[4:5]
	s_mov_b32 s27, 0

.LgB_done:
	buffer_inv sc1
	s_waitcnt vmcnt(0)
	s_mov_b64 exec, -1
	s_branch .Lg_to441
